# phase 3 work queue: sliding-window attention items (long) handed out before stick-breaking items (short) - longest-first order shortens the phase tail
# speedup vs baseline: 1.0056x; 1.0015x over previous
; DI int TID() { int t = threadIdx.x; asm volatile("" : "+v"(t)); return t; }
; DI unsigned char* WSP(const Params& P) { size_t z = 0; asm volatile("" : "+s"(z)); return P.ws + z; }
; DI void cmp2_tile(const Params& P, int l, int ct, u16* sA, u16* sB, float* sSS) {
;   const int tid = TID(), lane = tid & 63, w = tid >> 6, r16 = lane & 15, quad = lane >> 4, wm = w >> 1, wn = w & 1;
;   const int kv = ct >> 4, mt = ct & 15;
;   const u16* HID = (const u16*)(WSP(P) + WS_HID);
;   u16* OUT = (u16*)(WSP(P) + (kv ? WS_VC : WS_KC));
;   const u16* Ab = HID + ((long)kv * 2048 + mt * 128) * 256;
;   const u16* Bb = (const u16*)(WSP(P) + WS_W + WT_C2) + (long)kv * 64 * 256;
;   f32x4 acc[4][2];
;   gemm3<2>(acc, g3_ptr(Ab, 256, tid, 0, false), g3_ptr(Ab, 256, tid, 1, false), g3_ptr(Ab, 256, tid, 2, false), g3_ptr(Ab, 256, tid, 3, false), 64,
;            g3_ptr(Bb, 256, tid, 0, true), g3_ptr(Bb, 256, tid, 1, true), nullptr, nullptr, 256, sA);
; __global__ void __launch_bounds__(256, LB2) fwd_megakernel(Params P) {
;     ...
;         for (;;) {
;           int it = next_item(pc, &s_item); if (it >= 128 + 3072 + 64) break;
;           if (it < 128) gdn_p2_item(P, it, lds);
;           else if (it < 128 + 2048) sb_attn_item(P, it - 128, aQ, aK, aV);
;           else if (it < 128 + 3072) win_attn_item(P, it - 128 - 2048, aQ, aK, aV);
;           else if (it < 128 + 3072 + 32) s5_carry_item(P, l, it - 128 - 3072);
;           else cmp2_tile(P, l, it - 128 - 3072 - 32, sA, sB, lds + 17000);
.LBB0_266:
	s_or_b64 exec, exec, s[0:1]
	s_waitcnt lgkmcnt(0)
	s_barrier
	ds_read_b32 v0, v165
	s_movk_i32 s0, 0xcbf
	s_movk_i32 s4, 0xc00
	s_waitcnt lgkmcnt(0)
	v_add_u32_e32 v1, 0xffffff80, v0
	v_add_u32_e32 v2, 0x800, v0
	v_add_u32_e32 v3, 0xfffffc00, v0
	v_cmp_gt_u32_e64 s[2:3], s4, v1
	v_cmp_gt_u32_e32 vcc, 0x400, v1
	s_nop 1
	v_cndmask_b32_e64 v3, v0, v3, s[2:3]
	s_nop 0
	v_cndmask_b32_e32 v0, v3, v2, vcc
	v_cmp_lt_i32_e32 vcc, s0, v0
	v_readfirstlane_b32 s40, v0
	s_mov_b64 s[0:1], -1
	s_cbranch_vccnz .LBB0_261
	s_cmpk_gt_i32 s40, 0x7f
	s_cbranch_scc0 .LBB0_484
	s_cmpk_gt_u32 s40, 0x87f
	s_cbranch_scc0 .LBB0_462
	s_cmpk_gt_u32 s40, 0xc7f
	s_cbranch_scc0 .LBB0_442
	s_cmpk_gt_u32 s40, 0xc9f
	s_cbranch_scc0 .LBB0_438
	s_add_i32 s7, s40, 0xfffff360
	s_waitcnt vmcnt(6)
	v_mov_b32_e32 v44, v160
	s_lshr_b32 s46, s7, 4
	s_mov_b64 s[0:1], 0
	s_add_u32 s8, s70, s0
	s_addc_u32 s9, s71, s1
	s_lshl_b32 s4, s7, 7
	s_and_b32 s6, s4, 0x780
	s_lshl_b64 s[4:5], s[46:47], 20
	v_ashrrev_i32_e32 v10, 6, v44
	v_lshrrev_b32_e32 v1, 3, v44
	v_bfe_u32 v11, v44, 3, 3
	s_add_u32 s4, s8, s4
	v_lshl_or_b32 v0, v10, 5, v11
	v_bfe_u32 v1, v1, 1, 2
	s_addc_u32 s5, s9, s5
	s_lshl_b32 s8, s6, 9
	v_xor_b32_e32 v4, v1, v44
	v_ashrrev_i32_e32 v1, 31, v0
	s_add_u32 s4, s4, s8
	v_lshlrev_b64 v[2:3], 9, v[0:1]
	v_lshlrev_b32_e32 v1, 4, v4
	v_or_b32_e32 v4, 8, v0
	s_addc_u32 s5, s5, 0
	v_and_b32_e32 v162, 0x70, v1
	v_lshrrev_b32_e32 v1, 1, v4
	s_add_u32 s4, s4, 0x1ce00000
	v_xor_b32_e32 v1, v1, v44
	v_ashrrev_i32_e32 v5, 31, v4
	s_addc_u32 s5, s5, 0
	v_lshlrev_b64 v[4:5], 9, v[4:5]
	v_lshlrev_b32_e32 v1, 4, v1
	v_lshl_add_u64 v[4:5], s[4:5], 0, v[4:5]
	v_and_b32_e32 v6, 0x70, v1
	v_mov_b32_e32 v7, v163
	v_lshl_add_u64 v[4:5], v[4:5], 0, v[6:7]
	v_or_b32_e32 v6, 16, v0
	v_or_b32_e32 v0, 24, v0
	v_lshrrev_b32_e32 v1, 1, v0
	v_xor_b32_e32 v8, v1, v44
	v_ashrrev_i32_e32 v1, 31, v0
	s_mov_b64 s[0:1], 0
	s_mov_b64 s[8:9], 0
	v_lshlrev_b64 v[0:1], 9, v[0:1]
	v_lshlrev_b32_e32 v8, 4, v8
	s_add_u32 s10, s70, s8
	v_lshl_add_u64 v[0:1], s[4:5], 0, v[0:1]
	v_and_b32_e32 v8, 0x70, v8
	v_mov_b32_e32 v9, v163
	s_addc_u32 s11, s71, s9
	s_lshl_b64 s[8:9], s[46:47], 15
	v_lshl_add_u64 v[0:1], v[0:1], 0, v[8:9]
	v_lshl_or_b32 v8, v10, 4, v11
	s_add_u32 s8, s10, s8
	v_ashrrev_i32_e32 v9, 31, v8
	s_addc_u32 s9, s11, s9
	v_lshlrev_b64 v[10:11], 9, v[8:9]
	v_or_b32_e32 v8, 8, v8
	s_add_u32 s8, s8, 0x1f540000
	v_ashrrev_i32_e32 v7, 31, v6
	v_lshrrev_b32_e32 v9, 1, v8
	s_addc_u32 s9, s9, 0
	v_lshlrev_b64 v[6:7], 9, v[6:7]
	s_waitcnt vmcnt(4)
	v_xor_b32_e32 v12, v9, v44
	v_lshl_add_u64 v[2:3], s[4:5], 0, v[2:3]
	v_lshl_add_u64 v[6:7], s[4:5], 0, v[6:7]
	v_lshl_add_u64 v[10:11], s[8:9], 0, v[10:11]
	v_lshlrev_b32_e32 v12, 4, v12
	v_lshl_add_u64 v[2:3], v[2:3], 0, v[162:163]
	v_lshl_add_u64 v[6:7], v[6:7], 0, v[162:163]
	v_lshl_add_u64 v[10:11], v[10:11], 0, v[162:163]
	v_and_b32_e32 v162, 0x70, v12
	v_mov_b32_e32 v12, v160
	v_ashrrev_i32_e32 v9, 31, v8
	v_ashrrev_i32_e32 v13, 6, v12
	v_lshlrev_b64 v[8:9], 9, v[8:9]
	v_readfirstlane_b32 s5, v13
	s_barrier
	s_lshl_b32 s4, s5, 12
	s_mov_b32 m0, s4
	s_nop 0
	global_load_lds_dwordx4 v[2:3], off
	v_lshl_add_u64 v[8:9], s[8:9], 0, v[8:9]
	s_add_i32 s9, s4, 0x400
	s_mov_b32 m0, s9
	s_nop 0
	global_load_lds_dwordx4 v[4:5], off
	s_add_i32 s9, s4, 0x800
	s_mov_b32 m0, s9
	s_nop 0
	global_load_lds_dwordx4 v[6:7], off
	s_lshl_b32 s8, s5, 11
	s_add_i32 s9, s4, 0xc00
	s_mov_b32 m0, s9
	s_nop 0
	global_load_lds_dwordx4 v[0:1], off
	s_add_i32 s5, s8, 0x4000
	s_mov_b32 m0, s5
	s_nop 0
	global_load_lds_dwordx4 v[10:11], off
	s_addk_i32 s8, 0x4400
	v_lshl_add_u64 v[8:9], v[8:9], 0, v[162:163]
	v_lshrrev_b32_e32 v15, 1, v12
	v_and_b32_e32 v17, 15, v12
	s_mov_b32 m0, s8
	s_nop 0
	global_load_lds_dwordx4 v[8:9], off
	s_mov_b32 s8, 0x1ffffc0
	v_lshrrev_b32_e32 v14, 4, v12
	v_bfe_u32 v16, v12, 1, 3
	v_bfe_u32 v12, v12, 4, 2
	v_and_or_b32 v15, v15, s8, v17
	v_lshlrev_b32_e32 v13, 5, v13
	s_mov_b64 s[8:9], 0x80
	v_and_or_b32 v13, v13, 32, v17
	v_bitop3_b32 v14, v14, v16, 3 bitop3:0x6c
	v_bitop3_b32 v12, v12, v16, 4 bitop3:0x36
	v_lshl_add_u64 v[36:37], v[0:1], 0, s[8:9]
	v_mov_b32_e32 v0, 0
	s_mov_b64 s[2:3], 0
	v_lshlrev_b32_e32 v45, 3, v14
	v_lshlrev_b32_e32 v46, 7, v15
	v_lshlrev_b32_e32 v47, 7, v13
	v_lshlrev_b32_e32 v48, 3, v12
	v_lshl_add_u64 v[32:33], v[8:9], 0, s[8:9]
	v_lshl_add_u64 v[34:35], v[10:11], 0, s[8:9]
	v_lshl_add_u64 v[38:39], v[6:7], 0, s[8:9]
	v_lshl_add_u64 v[40:41], v[4:5], 0, s[8:9]
	v_lshl_add_u64 v[42:43], v[2:3], 0, s[8:9]
	s_mov_b32 s8, 0
	s_mov_b32 s9, 0
	v_mov_b32_e32 v1, v0
	v_mov_b32_e32 v2, v0
	v_mov_b32_e32 v3, v0
	v_mov_b32_e32 v4, v0
	v_mov_b32_e32 v5, v0
	v_mov_b32_e32 v6, v0
	v_mov_b32_e32 v7, v0
	v_mov_b32_e32 v8, v0
	v_mov_b32_e32 v9, v0
	v_mov_b32_e32 v10, v0
	v_mov_b32_e32 v11, v0
	v_mov_b32_e32 v12, v0
	v_mov_b32_e32 v13, v0
	v_mov_b32_e32 v14, v0
	v_mov_b32_e32 v15, v0
	v_mov_b32_e32 v16, v0
	v_mov_b32_e32 v17, v0
	v_mov_b32_e32 v18, v0
	v_mov_b32_e32 v19, v0
	v_mov_b32_e32 v20, v0
	v_mov_b32_e32 v21, v0
	v_mov_b32_e32 v22, v0
	v_mov_b32_e32 v23, v0
	v_mov_b32_e32 v24, v0
	v_mov_b32_e32 v25, v0
	v_mov_b32_e32 v26, v0
	v_mov_b32_e32 v27, v0
	v_mov_b32_e32 v28, v0
	v_mov_b32_e32 v29, v0
	v_mov_b32_e32 v30, v0
	v_mov_b32_e32 v31, v0
	s_branch .LBB0_273
